# v73 + early L2 writeback at the 5 global barriers + no preheader vmcnt(0) + P0/P7 gain-load hoist
# speedup vs baseline: 1.0100x; 1.0039x over previous
.LBB0_29:
	s_cmp_eq_u64 s[6:7], 0
	s_cbranch_scc1 .Lgain_skip_0
	v_lshlrev_b32_e32 v242, 2, v4
	global_load_dwordx2 v[226:227], v242, s[6:7]
	global_load_dwordx2 v[228:229], v242, s[6:7] offset:32
	global_load_dwordx2 v[230:231], v242, s[6:7] offset:64
	global_load_dwordx2 v[232:233], v242, s[6:7] offset:96
	global_load_dwordx2 v[234:235], v242, s[6:7] offset:128
	global_load_dwordx2 v[236:237], v242, s[6:7] offset:160
	global_load_dwordx2 v[238:239], v242, s[6:7] offset:192
	global_load_dwordx2 v[240:241], v242, s[6:7] offset:224

.LBB0_60:
	s_and_b64 vcc, exec, s[14:15]
	s_cbranch_vccnz .Lhave_next_0
	s_waitcnt vmcnt(0)
	s_branch .Lwaited_0
.Lhave_next_0:
	s_waitcnt vmcnt(16)
.Lwaited_0:
	s_cmp_lg_u64 s[6:7], 0
	s_cselect_b64 s[20:21], -1, 0
	s_cmp_eq_u64 s[6:7], 0
	v_mov_b32_e32 v153, v152
	v_lshlrev_b32_e32 v170, 2, v4
	v_mov_b32_e32 v156, v152
	v_mov_b32_e32 v157, v152
	s_cbranch_scc1 .LBB0_62
	v_mov_b32_e32 v156, v226
	v_mov_b32_e32 v157, v227
	v_pk_mul_f32 v[156:157], v[152:153], v[156:157]
.LBB0_62:
	v_mul_f32_e32 v137, v6, v156
	v_mul_f32_e32 v155, v10, v157
	v_cvt_pk_bf16_f32 v137, v137, v155
	ds_write_b32 v168, v137
	v_mul_f32_e32 v137, v7, v156
	v_mul_f32_e32 v155, v11, v157
	v_cvt_pk_bf16_f32 v137, v137, v155
	ds_write_b32 v168, v137 offset:132
	v_mul_f32_e32 v137, v8, v156
	v_mul_f32_e32 v155, v12, v157
	v_cvt_pk_bf16_f32 v137, v137, v155
	ds_write_b32 v168, v137 offset:264
	v_mul_f32_e32 v137, v9, v156
	v_mul_f32_e32 v155, v13, v157
	v_cvt_pk_bf16_f32 v137, v137, v155
	ds_write_b32 v168, v137 offset:396
	v_cndmask_b32_e64 v137, 0, 1, s[20:21]
	v_cmp_ne_u32_e64 s[4:5], 1, v137
	s_andn2_b64 vcc, exec, s[20:21]
	v_mov_b32_e32 v156, v152
	v_mov_b32_e32 v157, v152
	s_cbranch_vccnz .LBB0_64
	v_mov_b32_e32 v156, v228
	v_mov_b32_e32 v157, v229
	v_pk_mul_f32 v[156:157], v[152:153], v[156:157]
.LBB0_64:
	v_mul_f32_e32 v137, v14, v156
	v_mul_f32_e32 v155, v18, v157
	v_cvt_pk_bf16_f32 v137, v137, v155
	ds_write_b32 v168, v137 offset:16
	v_mul_f32_e32 v137, v15, v156
	v_mul_f32_e32 v155, v19, v157
	v_cvt_pk_bf16_f32 v137, v137, v155
	ds_write_b32 v168, v137 offset:148
	v_mul_f32_e32 v137, v16, v156
	v_mul_f32_e32 v155, v20, v157
	v_cvt_pk_bf16_f32 v137, v137, v155
	ds_write_b32 v168, v137 offset:280
	v_mul_f32_e32 v137, v17, v156
	v_mul_f32_e32 v155, v21, v157
	s_and_b64 vcc, exec, s[4:5]
	v_mov_b32_e32 v156, v152
	v_mov_b32_e32 v157, v152
	v_cvt_pk_bf16_f32 v137, v137, v155
	ds_write_b32 v168, v137 offset:412
	s_cbranch_vccnz .LBB0_66
	v_mov_b32_e32 v156, v230
	v_mov_b32_e32 v157, v231
	v_pk_mul_f32 v[156:157], v[152:153], v[156:157]
.LBB0_66:
	v_mul_f32_e32 v137, v22, v156
	v_mul_f32_e32 v155, v26, v157
	v_cvt_pk_bf16_f32 v137, v137, v155
	ds_write_b32 v168, v137 offset:32
	v_mul_f32_e32 v137, v23, v156
	v_mul_f32_e32 v155, v27, v157
	v_cvt_pk_bf16_f32 v137, v137, v155
	ds_write_b32 v168, v137 offset:164
	v_mul_f32_e32 v137, v24, v156
	v_mul_f32_e32 v155, v28, v157
	v_cvt_pk_bf16_f32 v137, v137, v155
	ds_write_b32 v168, v137 offset:296
	v_mul_f32_e32 v137, v25, v156
	v_mul_f32_e32 v155, v29, v157
	s_and_b64 vcc, exec, s[4:5]
	v_mov_b32_e32 v156, v152
	v_mov_b32_e32 v157, v152
	v_cvt_pk_bf16_f32 v137, v137, v155
	ds_write_b32 v168, v137 offset:428
	s_cbranch_vccnz .LBB0_68
	v_mov_b32_e32 v156, v232
	v_mov_b32_e32 v157, v233
	v_pk_mul_f32 v[156:157], v[152:153], v[156:157]
.LBB0_68:
	v_mul_f32_e32 v137, v30, v156
	v_mul_f32_e32 v155, v34, v157
	v_cvt_pk_bf16_f32 v137, v137, v155
	ds_write_b32 v168, v137 offset:48
	v_mul_f32_e32 v137, v31, v156
	v_mul_f32_e32 v155, v35, v157
	v_cvt_pk_bf16_f32 v137, v137, v155
	ds_write_b32 v168, v137 offset:180
	v_mul_f32_e32 v137, v32, v156
	v_mul_f32_e32 v155, v36, v157
	v_cvt_pk_bf16_f32 v137, v137, v155
	ds_write_b32 v168, v137 offset:312
	v_mul_f32_e32 v137, v33, v156
	v_mul_f32_e32 v155, v37, v157
	s_and_b64 vcc, exec, s[4:5]
	v_mov_b32_e32 v156, v152
	v_mov_b32_e32 v157, v152
	v_cvt_pk_bf16_f32 v137, v137, v155
	ds_write_b32 v168, v137 offset:444
	s_cbranch_vccnz .LBB0_70
	v_mov_b32_e32 v156, v234
	v_mov_b32_e32 v157, v235
	v_pk_mul_f32 v[156:157], v[152:153], v[156:157]
.LBB0_70:
	v_mul_f32_e32 v137, v38, v156
	v_mul_f32_e32 v155, v42, v157
	v_cvt_pk_bf16_f32 v137, v137, v155
	ds_write_b32 v168, v137 offset:64
	v_mul_f32_e32 v137, v39, v156
	v_mul_f32_e32 v155, v43, v157
	v_cvt_pk_bf16_f32 v137, v137, v155
	ds_write_b32 v168, v137 offset:196
	v_mul_f32_e32 v137, v40, v156
	v_mul_f32_e32 v155, v44, v157
	v_cvt_pk_bf16_f32 v137, v137, v155
	ds_write_b32 v168, v137 offset:328
	v_mul_f32_e32 v137, v41, v156
	v_mul_f32_e32 v155, v45, v157
	s_and_b64 vcc, exec, s[4:5]
	v_mov_b32_e32 v156, v152
	v_mov_b32_e32 v157, v152
	v_cvt_pk_bf16_f32 v137, v137, v155
	ds_write_b32 v168, v137 offset:460
	s_cbranch_vccnz .LBB0_72
	v_mov_b32_e32 v156, v236
	v_mov_b32_e32 v157, v237
	v_pk_mul_f32 v[156:157], v[152:153], v[156:157]
.LBB0_72:
	v_mul_f32_e32 v137, v46, v156
	v_mul_f32_e32 v155, v50, v157
	v_cvt_pk_bf16_f32 v137, v137, v155
	ds_write_b32 v168, v137 offset:80
	v_mul_f32_e32 v137, v47, v156
	v_mul_f32_e32 v155, v51, v157
	v_cvt_pk_bf16_f32 v137, v137, v155
	ds_write_b32 v168, v137 offset:212
	v_mul_f32_e32 v137, v48, v156
	v_mul_f32_e32 v155, v52, v157
	v_cvt_pk_bf16_f32 v137, v137, v155
	ds_write_b32 v168, v137 offset:344
	v_mul_f32_e32 v137, v49, v156
	v_mul_f32_e32 v155, v53, v157
	s_and_b64 vcc, exec, s[4:5]
	v_mov_b32_e32 v156, v152
	v_mov_b32_e32 v157, v152
	v_cvt_pk_bf16_f32 v137, v137, v155
	ds_write_b32 v168, v137 offset:476
	s_cbranch_vccnz .LBB0_74
	v_mov_b32_e32 v156, v238
	v_mov_b32_e32 v157, v239
	v_pk_mul_f32 v[156:157], v[152:153], v[156:157]
.LBB0_74:
	v_mul_f32_e32 v137, v54, v156
	v_mul_f32_e32 v155, v58, v157
	v_cvt_pk_bf16_f32 v137, v137, v155
	ds_write_b32 v168, v137 offset:96
	v_mul_f32_e32 v137, v55, v156
	v_mul_f32_e32 v155, v59, v157
	v_cvt_pk_bf16_f32 v137, v137, v155
	ds_write_b32 v168, v137 offset:228
	v_mul_f32_e32 v137, v56, v156
	v_mul_f32_e32 v155, v60, v157
	v_cvt_pk_bf16_f32 v137, v137, v155
	ds_write_b32 v168, v137 offset:360
	v_mul_f32_e32 v137, v57, v156
	v_mul_f32_e32 v155, v61, v157
	s_and_b64 vcc, exec, s[4:5]
	v_mov_b32_e32 v156, v152
	v_mov_b32_e32 v157, v152
	v_cvt_pk_bf16_f32 v137, v137, v155
	ds_write_b32 v168, v137 offset:492
	s_cbranch_vccnz .LBB0_76
	v_mov_b32_e32 v156, v240
	v_mov_b32_e32 v157, v241
	v_pk_mul_f32 v[156:157], v[152:153], v[156:157]
.LBB0_76:
	v_mul_f32_e32 v137, v62, v156
	v_mul_f32_e32 v153, v66, v157
	v_cvt_pk_bf16_f32 v137, v137, v153
	ds_write_b32 v168, v137 offset:112
	v_mul_f32_e32 v137, v63, v156
	v_mul_f32_e32 v153, v67, v157
	v_cvt_pk_bf16_f32 v137, v137, v153
	ds_write_b32 v168, v137 offset:244
	v_mul_f32_e32 v137, v64, v156
	v_mul_f32_e32 v153, v68, v157
	v_cvt_pk_bf16_f32 v137, v137, v153
	ds_write_b32 v168, v137 offset:376
	v_mul_f32_e32 v137, v65, v156
	v_mul_f32_e32 v153, v69, v157
	v_cvt_pk_bf16_f32 v137, v137, v153
	ds_write_b32 v168, v137 offset:508
	ds_read2_b32 v[172:173], v169 offset1:1
	ds_read2_b32 v[174:175], v169 offset0:2 offset1:3
	v_mad_u64_u32 v[156:157], s[4:5], s19, v134, 0
	v_add_u32_e32 v153, 0x420, v169
	v_lshl_add_u64 v[156:157], v[156:157], 1, s[8:9]
	v_add_u32_e32 v171, 0x428, v169
	ds_read2_b32 v[176:177], v153 offset1:1
	ds_read2_b32 v[178:179], v171 offset1:1
	v_lshl_add_u64 v[156:157], v[156:157], 0, v[2:3]
	s_waitcnt lgkmcnt(2)
	global_store_dwordx4 v[156:157], v[172:175], off
	v_mad_u64_u32 v[156:157], s[4:5], s19, v138, 0
	v_lshl_add_u64 v[156:157], v[156:157], 1, s[8:9]
	v_lshl_add_u64 v[156:157], v[156:157], 0, v[2:3]
	v_cmp_gt_i32_e32 vcc, s36, v140
	s_waitcnt lgkmcnt(0)
	global_store_dwordx4 v[156:157], v[176:179], off
	s_and_saveexec_b64 s[4:5], vcc
	s_cbranch_execz .LBB0_83
	v_add_u32_e32 v137, 0x840, v169
	v_add_u32_e32 v155, 0x848, v169
	ds_read2_b32 v[172:173], v137 offset1:1
	ds_read2_b32 v[174:175], v155 offset1:1
	v_mad_u64_u32 v[156:157], s[20:21], s19, v140, 0
	v_lshl_add_u64 v[156:157], v[156:157], 1, s[8:9]
	v_lshl_add_u64 v[156:157], v[156:157], 0, v[2:3]
	s_waitcnt lgkmcnt(0)
	global_store_dwordx4 v[156:157], v[172:175], off
	s_or_b64 exec, exec, s[4:5]
	v_cmp_gt_i32_e32 vcc, s36, v142
	s_and_saveexec_b64 s[4:5], vcc
	s_cbranch_execnz .LBB0_84

.Lrows_skipped_0:
	s_waitcnt vmcnt(0)
	s_branch .LBB0_59

.LBB0_89:
	s_cmp_eq_u64 s[10:11], 0
	s_cbranch_scc1 .Lgain_skip_1
	v_lshlrev_b32_e32 v242, 2, v4
	global_load_dwordx2 v[226:227], v242, s[10:11]
	global_load_dwordx2 v[228:229], v242, s[10:11] offset:32
	global_load_dwordx2 v[230:231], v242, s[10:11] offset:64
	global_load_dwordx2 v[232:233], v242, s[10:11] offset:96
	global_load_dwordx2 v[234:235], v242, s[10:11] offset:128
	global_load_dwordx2 v[236:237], v242, s[10:11] offset:160
	global_load_dwordx2 v[238:239], v242, s[10:11] offset:192
	global_load_dwordx2 v[240:241], v242, s[10:11] offset:224

.Lwaited_1:
	s_cmp_lg_u64 s[10:11], 0
	s_cselect_b64 s[20:21], -1, 0
	s_cmp_eq_u64 s[10:11], 0
	v_mov_b32_e32 v155, v154
	v_mov_b32_e32 v156, v154
	v_mov_b32_e32 v157, v154
	s_cbranch_scc1 .LBB0_122
	v_mov_b32_e32 v156, v226
	v_mov_b32_e32 v157, v227
	v_pk_mul_f32 v[156:157], v[154:155], v[156:157]
.LBB0_122:
	s_nop 0
	v_mul_f32_e32 v137, v70, v156
	v_mul_f32_e32 v172, v74, v157
	v_cvt_pk_bf16_f32 v137, v137, v172
	ds_write_b32 v168, v137
	v_mul_f32_e32 v137, v71, v156
	v_mul_f32_e32 v172, v75, v157
	v_cvt_pk_bf16_f32 v137, v137, v172
	ds_write_b32 v168, v137 offset:132
	v_mul_f32_e32 v137, v72, v156
	v_mul_f32_e32 v172, v76, v157
	v_cvt_pk_bf16_f32 v137, v137, v172
	ds_write_b32 v168, v137 offset:264
	v_mul_f32_e32 v137, v73, v156
	v_mul_f32_e32 v156, v77, v157
	v_cvt_pk_bf16_f32 v137, v137, v156
	ds_write_b32 v168, v137 offset:396
	v_cndmask_b32_e64 v137, 0, 1, s[20:21]
	v_cmp_ne_u32_e64 s[4:5], 1, v137
	s_andn2_b64 vcc, exec, s[20:21]
	v_mov_b32_e32 v156, v154
	v_mov_b32_e32 v157, v154
	s_cbranch_vccnz .LBB0_124
	v_mov_b32_e32 v156, v228
	v_mov_b32_e32 v157, v229
	v_pk_mul_f32 v[156:157], v[154:155], v[156:157]
.LBB0_124:
	s_nop 0
	v_mul_f32_e32 v137, v78, v156
	v_mul_f32_e32 v172, v82, v157
	v_cvt_pk_bf16_f32 v137, v137, v172
	ds_write_b32 v168, v137 offset:16
	v_mul_f32_e32 v137, v79, v156
	v_mul_f32_e32 v172, v83, v157
	v_cvt_pk_bf16_f32 v137, v137, v172
	ds_write_b32 v168, v137 offset:148
	v_mul_f32_e32 v137, v80, v156
	v_mul_f32_e32 v172, v84, v157
	v_cvt_pk_bf16_f32 v137, v137, v172
	ds_write_b32 v168, v137 offset:280
	v_mul_f32_e32 v137, v81, v156
	v_mul_f32_e32 v156, v85, v157
	v_cvt_pk_bf16_f32 v137, v137, v156
	s_and_b64 vcc, exec, s[4:5]
	v_mov_b32_e32 v156, v154
	v_mov_b32_e32 v157, v154
	ds_write_b32 v168, v137 offset:412
	s_cbranch_vccnz .LBB0_126
	v_mov_b32_e32 v156, v230
	v_mov_b32_e32 v157, v231
	v_pk_mul_f32 v[156:157], v[154:155], v[156:157]
.LBB0_126:
	s_nop 0
	v_mul_f32_e32 v137, v86, v156
	v_mul_f32_e32 v172, v90, v157
	v_cvt_pk_bf16_f32 v137, v137, v172
	ds_write_b32 v168, v137 offset:32
	v_mul_f32_e32 v137, v87, v156
	v_mul_f32_e32 v172, v91, v157
	v_cvt_pk_bf16_f32 v137, v137, v172
	ds_write_b32 v168, v137 offset:164
	v_mul_f32_e32 v137, v88, v156
	v_mul_f32_e32 v172, v92, v157
	v_cvt_pk_bf16_f32 v137, v137, v172
	ds_write_b32 v168, v137 offset:296
	v_mul_f32_e32 v137, v89, v156
	v_mul_f32_e32 v156, v93, v157
	v_cvt_pk_bf16_f32 v137, v137, v156
	s_and_b64 vcc, exec, s[4:5]
	v_mov_b32_e32 v156, v154
	v_mov_b32_e32 v157, v154
	ds_write_b32 v168, v137 offset:428
	s_cbranch_vccnz .LBB0_128
	v_mov_b32_e32 v156, v232
	v_mov_b32_e32 v157, v233
	v_pk_mul_f32 v[156:157], v[154:155], v[156:157]
.LBB0_128:
	s_nop 0
	v_mul_f32_e32 v137, v94, v156
	v_mul_f32_e32 v172, v98, v157
	v_cvt_pk_bf16_f32 v137, v137, v172
	ds_write_b32 v168, v137 offset:48
	v_mul_f32_e32 v137, v95, v156
	v_mul_f32_e32 v172, v99, v157
	v_cvt_pk_bf16_f32 v137, v137, v172
	ds_write_b32 v168, v137 offset:180
	v_mul_f32_e32 v137, v96, v156
	v_mul_f32_e32 v172, v100, v157
	v_cvt_pk_bf16_f32 v137, v137, v172
	ds_write_b32 v168, v137 offset:312
	v_mul_f32_e32 v137, v97, v156
	v_mul_f32_e32 v156, v101, v157
	v_cvt_pk_bf16_f32 v137, v137, v156
	s_and_b64 vcc, exec, s[4:5]
	v_mov_b32_e32 v156, v154
	v_mov_b32_e32 v157, v154
	ds_write_b32 v168, v137 offset:444
	s_cbranch_vccnz .LBB0_130
	v_mov_b32_e32 v156, v234
	v_mov_b32_e32 v157, v235
	v_pk_mul_f32 v[156:157], v[154:155], v[156:157]
.LBB0_130:
	s_nop 0
	v_mul_f32_e32 v137, v102, v156
	v_mul_f32_e32 v172, v106, v157
	v_cvt_pk_bf16_f32 v137, v137, v172
	ds_write_b32 v168, v137 offset:64
	v_mul_f32_e32 v137, v103, v156
	v_mul_f32_e32 v172, v107, v157
	v_cvt_pk_bf16_f32 v137, v137, v172
	ds_write_b32 v168, v137 offset:196
	v_mul_f32_e32 v137, v104, v156
	v_mul_f32_e32 v172, v108, v157
	v_cvt_pk_bf16_f32 v137, v137, v172
	ds_write_b32 v168, v137 offset:328
	v_mul_f32_e32 v137, v105, v156
	v_mul_f32_e32 v156, v109, v157
	v_cvt_pk_bf16_f32 v137, v137, v156
	s_and_b64 vcc, exec, s[4:5]
	v_mov_b32_e32 v156, v154
	v_mov_b32_e32 v157, v154
	ds_write_b32 v168, v137 offset:460
	s_cbranch_vccnz .LBB0_132
	v_mov_b32_e32 v156, v236
	v_mov_b32_e32 v157, v237
	v_pk_mul_f32 v[156:157], v[154:155], v[156:157]
.LBB0_132:
	s_nop 0
	v_mul_f32_e32 v137, v110, v156
	v_mul_f32_e32 v172, v114, v157
	v_cvt_pk_bf16_f32 v137, v137, v172
	ds_write_b32 v168, v137 offset:80
	v_mul_f32_e32 v137, v111, v156
	v_mul_f32_e32 v172, v115, v157
	v_cvt_pk_bf16_f32 v137, v137, v172
	ds_write_b32 v168, v137 offset:212
	v_mul_f32_e32 v137, v112, v156
	v_mul_f32_e32 v172, v116, v157
	v_cvt_pk_bf16_f32 v137, v137, v172
	ds_write_b32 v168, v137 offset:344
	v_mul_f32_e32 v137, v113, v156
	v_mul_f32_e32 v156, v117, v157
	v_cvt_pk_bf16_f32 v137, v137, v156
	s_and_b64 vcc, exec, s[4:5]
	v_mov_b32_e32 v156, v154
	v_mov_b32_e32 v157, v154
	ds_write_b32 v168, v137 offset:476
	s_cbranch_vccnz .LBB0_134
	v_mov_b32_e32 v156, v238
	v_mov_b32_e32 v157, v239
	v_pk_mul_f32 v[156:157], v[154:155], v[156:157]
.LBB0_134:
	s_nop 0
	v_mul_f32_e32 v137, v118, v156
	v_mul_f32_e32 v172, v122, v157
	v_cvt_pk_bf16_f32 v137, v137, v172
	ds_write_b32 v168, v137 offset:96
	v_mul_f32_e32 v137, v119, v156
	v_mul_f32_e32 v172, v123, v157
	v_cvt_pk_bf16_f32 v137, v137, v172
	ds_write_b32 v168, v137 offset:228
	v_mul_f32_e32 v137, v120, v156
	v_mul_f32_e32 v172, v124, v157
	v_cvt_pk_bf16_f32 v137, v137, v172
	ds_write_b32 v168, v137 offset:360
	v_mul_f32_e32 v137, v121, v156
	v_mul_f32_e32 v156, v125, v157
	v_cvt_pk_bf16_f32 v137, v137, v156
	s_and_b64 vcc, exec, s[4:5]
	v_mov_b32_e32 v156, v154
	v_mov_b32_e32 v157, v154
	ds_write_b32 v168, v137 offset:492
	s_cbranch_vccnz .LBB0_136
	v_mov_b32_e32 v156, v240
	v_mov_b32_e32 v157, v241
	v_pk_mul_f32 v[156:157], v[154:155], v[156:157]

.LBB0_967:
	s_cmp_eq_u64 s[8:9], 0
	s_cbranch_scc1 .Lgain_skip_2
	v_lshlrev_b32_e32 v242, 2, v164
	global_load_dwordx2 v[226:227], v242, s[8:9]
	global_load_dwordx2 v[228:229], v242, s[8:9] offset:32
	global_load_dwordx2 v[230:231], v242, s[8:9] offset:64
	global_load_dwordx2 v[232:233], v242, s[8:9] offset:96
	global_load_dwordx2 v[234:235], v242, s[8:9] offset:128
	global_load_dwordx2 v[236:237], v242, s[8:9] offset:160
	global_load_dwordx2 v[238:239], v242, s[8:9] offset:192
	global_load_dwordx2 v[240:241], v242, s[8:9] offset:224

.LBB0_1010:
	s_and_b64 vcc, exec, s[18:19]
	s_cbranch_vccnz .Lhave_next_2
	s_waitcnt vmcnt(0)
	s_branch .Lwaited_2

.Lwaited_2:
	s_cmp_lg_u64 s[8:9], 0
	s_cselect_b64 s[20:21], -1, 0
	s_cmp_eq_u64 s[8:9], 0
	v_mov_b32_e32 v183, v182
	v_lshlrev_b32_e32 v151, 2, v164
	v_mov_b32_e32 v186, v182
	v_mov_b32_e32 v187, v182
	s_cbranch_scc1 .LBB0_1012
	v_mov_b32_e32 v186, v226
	v_mov_b32_e32 v187, v227
	v_pk_mul_f32 v[186:187], v[182:183], v[186:187]
.LBB0_1012:
	v_mul_f32_e32 v153, v0, v186
	v_mul_f32_e32 v155, v4, v187
	v_cvt_pk_bf16_f32 v153, v153, v155
	ds_write_b32 v145, v153
	v_mul_f32_e32 v153, v1, v186
	v_mul_f32_e32 v155, v5, v187
	v_cvt_pk_bf16_f32 v153, v153, v155
	ds_write_b32 v145, v153 offset:132
	v_mul_f32_e32 v153, v2, v186
	v_mul_f32_e32 v155, v6, v187
	v_cvt_pk_bf16_f32 v153, v153, v155
	ds_write_b32 v145, v153 offset:264
	v_mul_f32_e32 v153, v3, v186
	v_mul_f32_e32 v155, v7, v187
	v_cvt_pk_bf16_f32 v153, v153, v155
	ds_write_b32 v145, v153 offset:396
	v_cndmask_b32_e64 v153, 0, 1, s[20:21]
	v_cmp_ne_u32_e64 s[6:7], 1, v153
	s_andn2_b64 vcc, exec, s[20:21]
	v_mov_b32_e32 v186, v182
	v_mov_b32_e32 v187, v182
	s_cbranch_vccnz .LBB0_1014
	v_mov_b32_e32 v186, v228
	v_mov_b32_e32 v187, v229
	v_pk_mul_f32 v[186:187], v[182:183], v[186:187]
.LBB0_1014:
	v_mul_f32_e32 v153, v8, v186
	v_mul_f32_e32 v155, v12, v187
	v_cvt_pk_bf16_f32 v153, v153, v155
	ds_write_b32 v145, v153 offset:16
	v_mul_f32_e32 v153, v9, v186
	v_mul_f32_e32 v155, v13, v187
	v_cvt_pk_bf16_f32 v153, v153, v155
	ds_write_b32 v145, v153 offset:148
	v_mul_f32_e32 v153, v10, v186
	v_mul_f32_e32 v155, v14, v187
	v_cvt_pk_bf16_f32 v153, v153, v155
	ds_write_b32 v145, v153 offset:280
	v_mul_f32_e32 v153, v11, v186
	v_mul_f32_e32 v155, v15, v187
	s_and_b64 vcc, exec, s[6:7]
	v_mov_b32_e32 v186, v182
	v_mov_b32_e32 v187, v182
	v_cvt_pk_bf16_f32 v153, v153, v155
	ds_write_b32 v145, v153 offset:412
	s_cbranch_vccnz .LBB0_1016
	v_mov_b32_e32 v186, v230
	v_mov_b32_e32 v187, v231
	v_pk_mul_f32 v[186:187], v[182:183], v[186:187]
.LBB0_1016:
	v_mul_f32_e32 v153, v16, v186
	v_mul_f32_e32 v155, v20, v187
	v_cvt_pk_bf16_f32 v153, v153, v155
	ds_write_b32 v145, v153 offset:32
	v_mul_f32_e32 v153, v17, v186
	v_mul_f32_e32 v155, v21, v187
	v_cvt_pk_bf16_f32 v153, v153, v155
	ds_write_b32 v145, v153 offset:164
	v_mul_f32_e32 v153, v18, v186
	v_mul_f32_e32 v155, v22, v187
	v_cvt_pk_bf16_f32 v153, v153, v155
	ds_write_b32 v145, v153 offset:296
	v_mul_f32_e32 v153, v19, v186
	v_mul_f32_e32 v155, v23, v187
	s_and_b64 vcc, exec, s[6:7]
	v_mov_b32_e32 v186, v182
	v_mov_b32_e32 v187, v182
	v_cvt_pk_bf16_f32 v153, v153, v155
	ds_write_b32 v145, v153 offset:428
	s_cbranch_vccnz .LBB0_1018
	v_mov_b32_e32 v186, v232
	v_mov_b32_e32 v187, v233
	v_pk_mul_f32 v[186:187], v[182:183], v[186:187]
.LBB0_1018:
	v_mul_f32_e32 v153, v24, v186
	v_mul_f32_e32 v155, v28, v187
	v_cvt_pk_bf16_f32 v153, v153, v155
	ds_write_b32 v145, v153 offset:48
	v_mul_f32_e32 v153, v25, v186
	v_mul_f32_e32 v155, v29, v187
	v_cvt_pk_bf16_f32 v153, v153, v155
	ds_write_b32 v145, v153 offset:180
	v_mul_f32_e32 v153, v26, v186
	v_mul_f32_e32 v155, v30, v187
	v_cvt_pk_bf16_f32 v153, v153, v155
	ds_write_b32 v145, v153 offset:312
	v_mul_f32_e32 v153, v27, v186
	v_mul_f32_e32 v155, v31, v187
	s_and_b64 vcc, exec, s[6:7]
	v_mov_b32_e32 v186, v182
	v_mov_b32_e32 v187, v182
	v_cvt_pk_bf16_f32 v153, v153, v155
	ds_write_b32 v145, v153 offset:444
	s_cbranch_vccnz .LBB0_1020
	v_mov_b32_e32 v186, v234
	v_mov_b32_e32 v187, v235
	v_pk_mul_f32 v[186:187], v[182:183], v[186:187]
.LBB0_1020:
	v_mul_f32_e32 v153, v36, v186
	v_mul_f32_e32 v155, v40, v187
	v_cvt_pk_bf16_f32 v153, v153, v155
	ds_write_b32 v145, v153 offset:64
	v_mul_f32_e32 v153, v37, v186
	v_mul_f32_e32 v155, v41, v187
	v_cvt_pk_bf16_f32 v153, v153, v155
	ds_write_b32 v145, v153 offset:196
	v_mul_f32_e32 v153, v38, v186
	v_mul_f32_e32 v155, v42, v187
	v_cvt_pk_bf16_f32 v153, v153, v155
	ds_write_b32 v145, v153 offset:328
	v_mul_f32_e32 v153, v39, v186
	v_mul_f32_e32 v155, v43, v187
	s_and_b64 vcc, exec, s[6:7]
	v_mov_b32_e32 v186, v182
	v_mov_b32_e32 v187, v182
	v_cvt_pk_bf16_f32 v153, v153, v155
	ds_write_b32 v145, v153 offset:460
	s_cbranch_vccnz .LBB0_1022
	v_mov_b32_e32 v186, v236
	v_mov_b32_e32 v187, v237
	v_pk_mul_f32 v[186:187], v[182:183], v[186:187]
.LBB0_1022:
	v_mul_f32_e32 v153, v44, v186
	v_mul_f32_e32 v155, v48, v187
	v_cvt_pk_bf16_f32 v153, v153, v155
	ds_write_b32 v145, v153 offset:80
	v_mul_f32_e32 v153, v45, v186
	v_mul_f32_e32 v155, v49, v187
	v_cvt_pk_bf16_f32 v153, v153, v155
	ds_write_b32 v145, v153 offset:212
	v_mul_f32_e32 v153, v46, v186
	v_mul_f32_e32 v155, v50, v187
	v_cvt_pk_bf16_f32 v153, v153, v155
	ds_write_b32 v145, v153 offset:344
	v_mul_f32_e32 v153, v47, v186
	v_mul_f32_e32 v155, v51, v187
	s_and_b64 vcc, exec, s[6:7]
	v_mov_b32_e32 v186, v182
	v_mov_b32_e32 v187, v182
	v_cvt_pk_bf16_f32 v153, v153, v155
	ds_write_b32 v145, v153 offset:476
	s_cbranch_vccnz .LBB0_1024
	v_mov_b32_e32 v186, v238
	v_mov_b32_e32 v187, v239
	v_pk_mul_f32 v[186:187], v[182:183], v[186:187]
.LBB0_1024:
	v_mul_f32_e32 v153, v52, v186
	v_mul_f32_e32 v155, v56, v187
	v_cvt_pk_bf16_f32 v153, v153, v155
	ds_write_b32 v145, v153 offset:96
	v_mul_f32_e32 v153, v53, v186
	v_mul_f32_e32 v155, v57, v187
	v_cvt_pk_bf16_f32 v153, v153, v155
	ds_write_b32 v145, v153 offset:228
	v_mul_f32_e32 v153, v54, v186
	v_mul_f32_e32 v155, v58, v187
	v_cvt_pk_bf16_f32 v153, v153, v155
	ds_write_b32 v145, v153 offset:360
	v_mul_f32_e32 v153, v55, v186
	v_mul_f32_e32 v155, v59, v187
	s_and_b64 vcc, exec, s[6:7]
	v_mov_b32_e32 v186, v182
	v_mov_b32_e32 v187, v182
	v_cvt_pk_bf16_f32 v153, v153, v155
	ds_write_b32 v145, v153 offset:492
	s_cbranch_vccnz .LBB0_1026
	v_mov_b32_e32 v186, v240
	v_mov_b32_e32 v187, v241
	v_pk_mul_f32 v[186:187], v[182:183], v[186:187]
.LBB0_1026:
	v_mul_f32_e32 v153, v32, v186
	v_mul_f32_e32 v155, v60, v187
	v_cvt_pk_bf16_f32 v153, v153, v155
	ds_write_b32 v145, v153 offset:112
	v_mul_f32_e32 v153, v33, v186
	v_mul_f32_e32 v155, v61, v187
	v_cvt_pk_bf16_f32 v153, v153, v155
	ds_write_b32 v145, v153 offset:244
	v_mul_f32_e32 v153, v34, v186
	v_mul_f32_e32 v155, v62, v187
	v_cvt_pk_bf16_f32 v153, v153, v155
	ds_write_b32 v145, v153 offset:376
	v_mul_f32_e32 v153, v35, v186
	v_mul_f32_e32 v155, v63, v187
	v_cvt_pk_bf16_f32 v153, v153, v155
	ds_write_b32 v145, v153 offset:508
	ds_read2_b32 v[186:187], v147 offset1:1
	ds_read2_b32 v[188:189], v147 offset0:2 offset1:3
	v_mad_u64_u32 v[190:191], s[6:7], s37, v130, 0
	v_lshl_add_u64 v[190:191], v[190:191], 1, s[10:11]
	ds_read2_b32 v[194:195], v149 offset1:1
	ds_read2_b32 v[196:197], v149 offset0:2 offset1:3
	v_lshl_add_u64 v[190:191], v[190:191], 0, v[166:167]
	s_waitcnt lgkmcnt(2)
	global_store_dwordx4 v[190:191], v[186:189], off
	v_cmp_gt_i32_e32 vcc, s39, v170
	s_nop 0
	v_mad_u64_u32 v[186:187], s[6:7], s37, v168, 0
	v_lshl_add_u64 v[186:187], v[186:187], 1, s[10:11]
	v_lshl_add_u64 v[186:187], v[186:187], 0, v[166:167]
	s_waitcnt lgkmcnt(0)
	global_store_dwordx4 v[186:187], v[194:197], off
	s_and_saveexec_b64 s[6:7], vcc
	s_cbranch_execz .LBB0_1033
	v_add_u32_e32 v153, v129, v131
	ds_read2_b32 v[186:187], v153 offset1:1
	ds_read2_b32 v[188:189], v153 offset0:2 offset1:3
	v_mad_u64_u32 v[190:191], s[20:21], s37, v170, 0
	v_lshl_add_u64 v[190:191], v[190:191], 1, s[10:11]
	v_lshl_add_u64 v[190:191], v[190:191], 0, v[166:167]
	s_waitcnt lgkmcnt(0)
	global_store_dwordx4 v[190:191], v[186:189], off
	s_or_b64 exec, exec, s[6:7]
	v_cmp_gt_i32_e32 vcc, s39, v172
	s_and_saveexec_b64 s[6:7], vcc
	s_cbranch_execnz .LBB0_1034

.LBB0_1039:
	s_cmp_eq_u64 s[12:13], 0
	s_cbranch_scc1 .Lgain_skip_3
	v_lshlrev_b32_e32 v242, 2, v164
	global_load_dwordx2 v[226:227], v242, s[12:13]
	global_load_dwordx2 v[228:229], v242, s[12:13] offset:32
	global_load_dwordx2 v[230:231], v242, s[12:13] offset:64
	global_load_dwordx2 v[232:233], v242, s[12:13] offset:96
	global_load_dwordx2 v[234:235], v242, s[12:13] offset:128
	global_load_dwordx2 v[236:237], v242, s[12:13] offset:160
	global_load_dwordx2 v[238:239], v242, s[12:13] offset:192
	global_load_dwordx2 v[240:241], v242, s[12:13] offset:224

.Lwaited_3:
	s_cmp_lg_u64 s[12:13], 0
	s_cselect_b64 s[20:21], -1, 0
	s_cmp_eq_u64 s[12:13], 0
	v_mov_b32_e32 v185, v184
	v_mov_b32_e32 v186, v184
	v_mov_b32_e32 v187, v184
	s_cbranch_scc1 .LBB0_1085
	v_mov_b32_e32 v186, v226
	v_mov_b32_e32 v187, v227
	v_pk_mul_f32 v[186:187], v[184:185], v[186:187]
.LBB0_1085:
	s_nop 0
	v_mul_f32_e32 v153, v64, v186
	v_mul_f32_e32 v155, v68, v187
	v_cvt_pk_bf16_f32 v153, v153, v155
	ds_write_b32 v145, v153
	v_mul_f32_e32 v153, v65, v186
	v_mul_f32_e32 v155, v69, v187
	v_cvt_pk_bf16_f32 v153, v153, v155
	ds_write_b32 v145, v153 offset:132
	v_mul_f32_e32 v153, v66, v186
	v_mul_f32_e32 v155, v70, v187
	v_cvt_pk_bf16_f32 v153, v153, v155
	ds_write_b32 v145, v153 offset:264
	v_mul_f32_e32 v153, v67, v186
	v_mul_f32_e32 v155, v71, v187
	v_cvt_pk_bf16_f32 v153, v153, v155
	ds_write_b32 v145, v153 offset:396
	v_cndmask_b32_e64 v153, 0, 1, s[20:21]
	v_cmp_ne_u32_e64 s[6:7], 1, v153
	s_andn2_b64 vcc, exec, s[20:21]
	v_mov_b32_e32 v186, v184
	v_mov_b32_e32 v187, v184
	s_cbranch_vccnz .LBB0_1087
	v_mov_b32_e32 v186, v228
	v_mov_b32_e32 v187, v229
	v_pk_mul_f32 v[186:187], v[184:185], v[186:187]
.LBB0_1087:
	s_nop 0
	v_mul_f32_e32 v153, v72, v186
	v_mul_f32_e32 v155, v76, v187
	v_cvt_pk_bf16_f32 v153, v153, v155
	ds_write_b32 v145, v153 offset:16
	v_mul_f32_e32 v153, v73, v186
	v_mul_f32_e32 v155, v77, v187
	v_cvt_pk_bf16_f32 v153, v153, v155
	ds_write_b32 v145, v153 offset:148
	v_mul_f32_e32 v153, v74, v186
	v_mul_f32_e32 v155, v78, v187
	v_cvt_pk_bf16_f32 v153, v153, v155
	ds_write_b32 v145, v153 offset:280
	v_mul_f32_e32 v153, v75, v186
	v_mul_f32_e32 v155, v79, v187
	s_and_b64 vcc, exec, s[6:7]
	v_mov_b32_e32 v186, v184
	v_mov_b32_e32 v187, v184
	v_cvt_pk_bf16_f32 v153, v153, v155
	ds_write_b32 v145, v153 offset:412
	s_cbranch_vccnz .LBB0_1089
	v_mov_b32_e32 v186, v230
	v_mov_b32_e32 v187, v231
	v_pk_mul_f32 v[186:187], v[184:185], v[186:187]
.LBB0_1089:
	s_nop 0
	v_mul_f32_e32 v153, v80, v186
	v_mul_f32_e32 v155, v84, v187
	v_cvt_pk_bf16_f32 v153, v153, v155
	ds_write_b32 v145, v153 offset:32
	v_mul_f32_e32 v153, v81, v186
	v_mul_f32_e32 v155, v85, v187
	v_cvt_pk_bf16_f32 v153, v153, v155
	ds_write_b32 v145, v153 offset:164
	v_mul_f32_e32 v153, v82, v186
	v_mul_f32_e32 v155, v86, v187
	v_cvt_pk_bf16_f32 v153, v153, v155
	ds_write_b32 v145, v153 offset:296
	v_mul_f32_e32 v153, v83, v186
	v_mul_f32_e32 v155, v87, v187
	s_and_b64 vcc, exec, s[6:7]
	v_mov_b32_e32 v186, v184
	v_mov_b32_e32 v187, v184
	v_cvt_pk_bf16_f32 v153, v153, v155
	ds_write_b32 v145, v153 offset:428
	s_cbranch_vccnz .LBB0_1091
	v_mov_b32_e32 v186, v232
	v_mov_b32_e32 v187, v233
	v_pk_mul_f32 v[186:187], v[184:185], v[186:187]
.LBB0_1091:
	s_nop 0
	v_mul_f32_e32 v153, v88, v186
	v_mul_f32_e32 v155, v92, v187
	v_cvt_pk_bf16_f32 v153, v153, v155
	ds_write_b32 v145, v153 offset:48
	v_mul_f32_e32 v153, v89, v186
	v_mul_f32_e32 v155, v93, v187
	v_cvt_pk_bf16_f32 v153, v153, v155
	ds_write_b32 v145, v153 offset:180
	v_mul_f32_e32 v153, v90, v186
	v_mul_f32_e32 v155, v94, v187
	v_cvt_pk_bf16_f32 v153, v153, v155
	ds_write_b32 v145, v153 offset:312
	v_mul_f32_e32 v153, v91, v186
	v_mul_f32_e32 v155, v95, v187
	s_and_b64 vcc, exec, s[6:7]
	v_mov_b32_e32 v186, v184
	v_mov_b32_e32 v187, v184
	v_cvt_pk_bf16_f32 v153, v153, v155
	ds_write_b32 v145, v153 offset:444
	s_cbranch_vccnz .LBB0_1093
	v_mov_b32_e32 v186, v234
	v_mov_b32_e32 v187, v235
	v_pk_mul_f32 v[186:187], v[184:185], v[186:187]
.LBB0_1093:
	s_nop 0
	v_mul_f32_e32 v153, v96, v186
	v_mul_f32_e32 v155, v100, v187
	v_cvt_pk_bf16_f32 v153, v153, v155
	ds_write_b32 v145, v153 offset:64
	v_mul_f32_e32 v153, v97, v186
	v_mul_f32_e32 v155, v101, v187
	v_cvt_pk_bf16_f32 v153, v153, v155
	ds_write_b32 v145, v153 offset:196
	v_mul_f32_e32 v153, v98, v186
	v_mul_f32_e32 v155, v102, v187
	v_cvt_pk_bf16_f32 v153, v153, v155
	ds_write_b32 v145, v153 offset:328
	v_mul_f32_e32 v153, v99, v186
	v_mul_f32_e32 v155, v103, v187
	s_and_b64 vcc, exec, s[6:7]
	v_mov_b32_e32 v186, v184
	v_mov_b32_e32 v187, v184
	v_cvt_pk_bf16_f32 v153, v153, v155
	ds_write_b32 v145, v153 offset:460
	s_cbranch_vccnz .LBB0_1095
	v_mov_b32_e32 v186, v236
	v_mov_b32_e32 v187, v237
	v_pk_mul_f32 v[186:187], v[184:185], v[186:187]
.LBB0_1095:
	s_nop 0
	v_mul_f32_e32 v153, v104, v186
	v_mul_f32_e32 v155, v108, v187
	v_cvt_pk_bf16_f32 v153, v153, v155
	ds_write_b32 v145, v153 offset:80
	v_mul_f32_e32 v153, v105, v186
	v_mul_f32_e32 v155, v109, v187
	v_cvt_pk_bf16_f32 v153, v153, v155
	ds_write_b32 v145, v153 offset:212
	v_mul_f32_e32 v153, v106, v186
	v_mul_f32_e32 v155, v110, v187
	v_cvt_pk_bf16_f32 v153, v153, v155
	ds_write_b32 v145, v153 offset:344
	v_mul_f32_e32 v153, v107, v186
	v_mul_f32_e32 v155, v111, v187
	s_and_b64 vcc, exec, s[6:7]
	v_mov_b32_e32 v186, v184
	v_mov_b32_e32 v187, v184
	v_cvt_pk_bf16_f32 v153, v153, v155
	ds_write_b32 v145, v153 offset:476
	s_cbranch_vccnz .LBB0_1097
	v_mov_b32_e32 v186, v238
	v_mov_b32_e32 v187, v239
	v_pk_mul_f32 v[186:187], v[184:185], v[186:187]
.LBB0_1097:
	s_nop 0
	v_mul_f32_e32 v153, v112, v186
	v_mul_f32_e32 v155, v116, v187
	v_cvt_pk_bf16_f32 v153, v153, v155
	ds_write_b32 v145, v153 offset:96
	v_mul_f32_e32 v153, v113, v186
	v_mul_f32_e32 v155, v117, v187
	v_cvt_pk_bf16_f32 v153, v153, v155
	ds_write_b32 v145, v153 offset:228
	v_mul_f32_e32 v153, v114, v186
	v_mul_f32_e32 v155, v118, v187
	v_cvt_pk_bf16_f32 v153, v153, v155
	ds_write_b32 v145, v153 offset:360
	v_mul_f32_e32 v153, v115, v186
	v_mul_f32_e32 v155, v119, v187
	s_and_b64 vcc, exec, s[6:7]
	v_mov_b32_e32 v186, v184
	v_mov_b32_e32 v187, v184
	v_cvt_pk_bf16_f32 v153, v153, v155
	ds_write_b32 v145, v153 offset:492
	s_cbranch_vccnz .LBB0_1099
	v_mov_b32_e32 v186, v240
	v_mov_b32_e32 v187, v241
	v_pk_mul_f32 v[186:187], v[184:185], v[186:187]
